# sparse attention QK segment: second accumulator's mask start values built under the first accumulator's MFMA chain; one continuous 16-MFMA segment with the second chain's K fragments read meanwhile
# speedup vs baseline: 1.0091x; 1.0062x over previous
.LBB0_67:
	s_mul_i32 s0, s49, 0x8c00
	s_add_i32 s47, s0, 0
	v_add3_u32 v217, s47, v209, v210
	v_lshrrev_b32_e32 v218, v186, v202
	v_lshrrev_b32_e32 v203, v186, v203
	s_and_saveexec_b64 s[0:1], s[6:7]
	s_xor_b64 s[0:1], exec, s[0:1]
	s_cbranch_execz .LBB0_71
	v_bfe_i32 v66, v218, 0, 1
	v_bfe_i32 v67, v218, 1, 1
	v_bfe_i32 v68, v218, 2, 1
	v_bfe_i32 v69, v218, 3, 1
	v_bfe_i32 v70, v218, 8, 1
	v_bfe_i32 v71, v218, 9, 1
	v_bfe_i32 v72, v218, 10, 1
	v_bfe_i32 v73, v218, 11, 1
	v_bfe_i32 v74, v218, 16, 1
	v_bfe_i32 v75, v218, 17, 1
	v_bfe_i32 v76, v218, 18, 1
	v_bfe_i32 v77, v218, 19, 1
	v_bfe_i32 v78, v218, 24, 1
	v_bfe_i32 v79, v218, 25, 1
	v_bfe_i32 v80, v218, 26, 1
	v_bfe_i32 v81, v218, 27, 1
	ds_read_b128 v[218:221], v217
	ds_read_b128 v[222:225], v217 offset:32
	ds_read_b128 v[226:229], v217 offset:64
	ds_read_b128 v[232:235], v217 offset:96
	ds_read_b128 v[236:239], v217 offset:128
	ds_read_b128 v[248:251], v217 offset:160
	ds_read_b128 v[240:243], v217 offset:192
	ds_read_b128 v[174:177], v217 offset:224
	v_bfi_b32 v66, v66, v230, v231
	v_bfi_b32 v67, v67, v230, v231
	v_bfi_b32 v68, v68, v230, v231
	v_bfi_b32 v69, v69, v230, v231
	v_bfi_b32 v70, v70, v230, v231
	v_bfi_b32 v71, v71, v230, v231
	v_bfi_b32 v72, v72, v230, v231
	v_bfi_b32 v73, v73, v230, v231
	v_bfi_b32 v74, v74, v230, v231
	v_bfi_b32 v75, v75, v230, v231
	v_bfi_b32 v76, v76, v230, v231
	v_bfi_b32 v77, v77, v230, v231
	v_bfi_b32 v78, v78, v230, v231
	v_bfi_b32 v79, v79, v230, v231
	v_bfi_b32 v80, v80, v230, v231
	v_bfi_b32 v81, v81, v230, v231
	s_setprio 1
	s_waitcnt lgkmcnt(7)
	v_mfma_f32_32x32x16_bf16 v[66:81], v[218:221], v[98:101], v[66:81]
	ds_read_b128 v[218:221], v217 offset:8704
	v_bfe_i32 v82, v203, 0, 1
	v_bfe_i32 v83, v203, 1, 1
	v_bfe_i32 v84, v203, 2, 1
	v_bfe_i32 v85, v203, 3, 1
	v_bfe_i32 v86, v203, 8, 1
	s_waitcnt lgkmcnt(7)
	v_mfma_f32_32x32x16_bf16 v[66:81], v[222:225], v[102:105], v[66:81]
	ds_read_b128 v[222:225], v217 offset:8736
	v_bfe_i32 v87, v203, 9, 1
	v_bfe_i32 v88, v203, 10, 1
	v_bfe_i32 v89, v203, 11, 1
	v_bfe_i32 v90, v203, 16, 1
	v_bfe_i32 v91, v203, 17, 1
	s_waitcnt lgkmcnt(7)
	v_mfma_f32_32x32x16_bf16 v[66:81], v[226:229], v[106:109], v[66:81]
	ds_read_b128 v[226:229], v217 offset:8768
	v_bfe_i32 v92, v203, 18, 1
	v_bfe_i32 v93, v203, 19, 1
	v_bfe_i32 v94, v203, 24, 1
	v_bfe_i32 v95, v203, 25, 1
	v_bfe_i32 v96, v203, 26, 1
	s_waitcnt lgkmcnt(7)
	v_mfma_f32_32x32x16_bf16 v[66:81], v[232:235], v[110:113], v[66:81]
	ds_read_b128 v[232:235], v217 offset:8800
	v_bfe_i32 v97, v203, 27, 1
	v_bfi_b32 v82, v82, v230, v231
	v_bfi_b32 v83, v83, v230, v231
	v_bfi_b32 v84, v84, v230, v231
	v_bfi_b32 v85, v85, v230, v231
	s_waitcnt lgkmcnt(7)
	v_mfma_f32_32x32x16_bf16 v[66:81], v[236:239], v[114:117], v[66:81]
	ds_read_b128 v[236:239], v217 offset:8832
	v_bfi_b32 v86, v86, v230, v231
	v_bfi_b32 v87, v87, v230, v231
	v_bfi_b32 v88, v88, v230, v231
	v_bfi_b32 v89, v89, v230, v231
	s_waitcnt lgkmcnt(7)
	v_mfma_f32_32x32x16_bf16 v[66:81], v[248:251], v[118:121], v[66:81]
	ds_read_b128 v[248:251], v217 offset:8864
	v_bfi_b32 v90, v90, v230, v231
	v_bfi_b32 v91, v91, v230, v231
	v_bfi_b32 v92, v92, v230, v231
	v_bfi_b32 v93, v93, v230, v231
	s_waitcnt lgkmcnt(7)
	v_mfma_f32_32x32x16_bf16 v[66:81], v[240:243], v[122:125], v[66:81]
	ds_read_b128 v[240:243], v217 offset:8896
	v_bfi_b32 v94, v94, v230, v231
	v_bfi_b32 v95, v95, v230, v231
	v_bfi_b32 v96, v96, v230, v231
	v_bfi_b32 v97, v97, v230, v231
	s_waitcnt lgkmcnt(7)
	v_mfma_f32_32x32x16_bf16 v[66:81], v[174:177], v[126:129], v[66:81]
	ds_read_b128 v[174:177], v217 offset:8928
	s_waitcnt lgkmcnt(7)
	v_mfma_f32_32x32x16_bf16 v[82:97], v[218:221], v[98:101], v[82:97]
	s_waitcnt lgkmcnt(6)
	v_mfma_f32_32x32x16_bf16 v[82:97], v[222:225], v[102:105], v[82:97]
	s_waitcnt lgkmcnt(5)
	v_mfma_f32_32x32x16_bf16 v[82:97], v[226:229], v[106:109], v[82:97]
	s_waitcnt lgkmcnt(4)
	v_mfma_f32_32x32x16_bf16 v[82:97], v[232:235], v[110:113], v[82:97]
	s_waitcnt lgkmcnt(3)
	v_mfma_f32_32x32x16_bf16 v[82:97], v[236:239], v[114:117], v[82:97]
	s_waitcnt lgkmcnt(2)
	v_mfma_f32_32x32x16_bf16 v[82:97], v[248:251], v[118:121], v[82:97]
	s_waitcnt lgkmcnt(1)
	v_mfma_f32_32x32x16_bf16 v[82:97], v[240:243], v[122:125], v[82:97]
	s_waitcnt lgkmcnt(0)
	v_mfma_f32_32x32x16_bf16 v[82:97], v[174:177], v[126:129], v[82:97]
	s_setprio 0
	v_max3_f32 v174, v231, v66, v82
	s_nop 0
	v_max3_f32 v174, v174, v67, v83
	s_nop 0
	v_max3_f32 v174, v174, v68, v84
	s_nop 0
	v_max3_f32 v174, v174, v69, v85
	s_nop 0
	v_max3_f32 v174, v174, v70, v86
	s_nop 0
	v_max3_f32 v174, v174, v71, v87
	s_nop 0
	v_max3_f32 v174, v174, v72, v88
	s_nop 0
	v_max3_f32 v174, v174, v73, v89
	s_nop 0
	v_max3_f32 v174, v174, v74, v90
	s_nop 0
	v_max3_f32 v174, v174, v75, v91
	s_nop 0
	v_max3_f32 v174, v174, v76, v92
	s_nop 0
	v_max3_f32 v174, v174, v77, v93
	s_nop 0
	v_max3_f32 v174, v174, v78, v94
	s_nop 0
	v_max3_f32 v174, v174, v79, v95
	s_nop 0
	v_max3_f32 v174, v174, v80, v96
	s_nop 0
	v_max3_f32 v174, v174, v81, v97
	s_nop 0
	v_mov_b32_e32 v175, v174
	s_nop 1
	v_permlane32_swap_b32_e32 v174, v175
	v_max_f32_e32 v174, v174, v175
	v_cmp_gt_f32_e32 vcc, v174, v245
	s_cmp_eq_u64 vcc, 0
	s_cbranch_scc1 .Lsmf_0
	v_cndmask_b32_e32 v203, 0, v174, vcc
	v_mov_b32_e32 v175, 0x41000000
	v_cndmask_b32_e32 v245, v245, v175, vcc
	v_sub_f32_e32 v230, v230, v203
	v_max_f32_e32 v175, 0, v203
	v_exp_f32_e64 v202, -v175
	s_nop 0
	v_pk_mul_f32 v[64:65], v[64:65], v[202:203] op_sel_hi:[1,0]
	v_pk_mul_f32 v[62:63], v[62:63], v[202:203] op_sel_hi:[1,0]
	v_pk_mul_f32 v[60:61], v[60:61], v[202:203] op_sel_hi:[1,0]
	v_pk_mul_f32 v[58:59], v[58:59], v[202:203] op_sel_hi:[1,0]
	v_pk_mul_f32 v[56:57], v[56:57], v[202:203] op_sel_hi:[1,0]
	v_pk_mul_f32 v[54:55], v[54:55], v[202:203] op_sel_hi:[1,0]
	v_pk_mul_f32 v[52:53], v[52:53], v[202:203] op_sel_hi:[1,0]
	v_pk_mul_f32 v[50:51], v[50:51], v[202:203] op_sel_hi:[1,0]
	v_pk_mul_f32 v[48:49], v[48:49], v[202:203] op_sel_hi:[1,0]
	v_pk_mul_f32 v[46:47], v[46:47], v[202:203] op_sel_hi:[1,0]
	v_pk_mul_f32 v[44:45], v[44:45], v[202:203] op_sel_hi:[1,0]
	v_pk_mul_f32 v[42:43], v[42:43], v[202:203] op_sel_hi:[1,0]
	v_pk_mul_f32 v[40:41], v[40:41], v[202:203] op_sel_hi:[1,0]
	v_pk_mul_f32 v[38:39], v[38:39], v[202:203] op_sel_hi:[1,0]
	v_pk_mul_f32 v[36:37], v[36:37], v[202:203] op_sel_hi:[1,0]
	v_pk_mul_f32 v[34:35], v[34:35], v[202:203] op_sel_hi:[1,0]
	v_pk_mul_f32 v[32:33], v[32:33], v[202:203] op_sel_hi:[1,0]
	v_pk_mul_f32 v[30:31], v[30:31], v[202:203] op_sel_hi:[1,0]
	v_pk_mul_f32 v[28:29], v[28:29], v[202:203] op_sel_hi:[1,0]
	v_pk_mul_f32 v[26:27], v[26:27], v[202:203] op_sel_hi:[1,0]
	v_pk_mul_f32 v[24:25], v[24:25], v[202:203] op_sel_hi:[1,0]
	v_pk_mul_f32 v[22:23], v[22:23], v[202:203] op_sel_hi:[1,0]
	v_pk_mul_f32 v[20:21], v[20:21], v[202:203] op_sel_hi:[1,0]
	v_pk_mul_f32 v[18:19], v[18:19], v[202:203] op_sel_hi:[1,0]
	v_pk_mul_f32 v[16:17], v[16:17], v[202:203] op_sel_hi:[1,0]
	v_pk_mul_f32 v[14:15], v[14:15], v[202:203] op_sel_hi:[1,0]
	v_pk_mul_f32 v[12:13], v[12:13], v[202:203] op_sel_hi:[1,0]
	v_pk_mul_f32 v[10:11], v[10:11], v[202:203] op_sel_hi:[1,0]
	v_pk_mul_f32 v[8:9], v[8:9], v[202:203] op_sel_hi:[1,0]
	v_pk_mul_f32 v[6:7], v[6:7], v[202:203] op_sel_hi:[1,0]
	v_pk_mul_f32 v[4:5], v[4:5], v[202:203] op_sel_hi:[1,0]
	v_pk_mul_f32 v[2:3], v[2:3], v[202:203] op_sel_hi:[1,0]

.LBB0_77:
	v_bfe_i32 v66, v218, 0, 1
	v_bfe_i32 v67, v218, 1, 1
	v_bfe_i32 v68, v218, 2, 1
	v_bfe_i32 v69, v218, 3, 1
	v_bfe_i32 v70, v218, 8, 1
	v_bfe_i32 v71, v218, 9, 1
	v_bfe_i32 v72, v218, 10, 1
	v_bfe_i32 v73, v218, 11, 1
	v_bfe_i32 v74, v218, 16, 1
	v_bfe_i32 v75, v218, 17, 1
	v_bfe_i32 v76, v218, 18, 1
	v_bfe_i32 v77, v218, 19, 1
	v_bfe_i32 v78, v218, 24, 1
	v_bfe_i32 v79, v218, 25, 1
	v_bfe_i32 v80, v218, 26, 1
	v_bfe_i32 v81, v218, 27, 1
	ds_read_b128 v[174:177], v217
	ds_read_b128 v[218:221], v217 offset:32
	ds_read_b128 v[222:225], v217 offset:64
	ds_read_b128 v[226:229], v217 offset:96
	ds_read_b128 v[232:235], v217 offset:128
	ds_read_b128 v[236:239], v217 offset:160
	ds_read_b128 v[240:243], v217 offset:192
	ds_read_b128 v[248:251], v217 offset:224
	v_bfi_b32 v66, v66, v230, v231
	v_bfi_b32 v67, v67, v230, v231
	v_bfi_b32 v68, v68, v230, v231
	v_bfi_b32 v69, v69, v230, v231
	v_bfi_b32 v70, v70, v230, v231
	v_bfi_b32 v71, v71, v230, v231
	v_bfi_b32 v72, v72, v230, v231
	v_bfi_b32 v73, v73, v230, v231
	v_bfi_b32 v74, v74, v230, v231
	v_bfi_b32 v75, v75, v230, v231
	v_bfi_b32 v76, v76, v230, v231
	v_bfi_b32 v77, v77, v230, v231
	v_bfi_b32 v78, v78, v230, v231
	v_bfi_b32 v79, v79, v230, v231
	v_bfi_b32 v80, v80, v230, v231
	v_bfi_b32 v81, v81, v230, v231
	s_setprio 1
	s_waitcnt lgkmcnt(7)
	v_mfma_f32_32x32x16_bf16 v[66:81], v[174:177], v[98:101], v[66:81]
	ds_read_b128 v[174:177], v217 offset:8704
	v_bfe_i32 v82, v203, 0, 1
	v_bfe_i32 v83, v203, 1, 1
	v_bfe_i32 v84, v203, 2, 1
	v_bfe_i32 v85, v203, 3, 1
	v_bfe_i32 v86, v203, 8, 1
	s_waitcnt lgkmcnt(7)
	v_mfma_f32_32x32x16_bf16 v[66:81], v[218:221], v[102:105], v[66:81]
	ds_read_b128 v[218:221], v217 offset:8736
	v_bfe_i32 v87, v203, 9, 1
	v_bfe_i32 v88, v203, 10, 1
	v_bfe_i32 v89, v203, 11, 1
	v_bfe_i32 v90, v203, 16, 1
	v_bfe_i32 v91, v203, 17, 1
	s_waitcnt lgkmcnt(7)
	v_mfma_f32_32x32x16_bf16 v[66:81], v[222:225], v[106:109], v[66:81]
	ds_read_b128 v[222:225], v217 offset:8768
	v_bfe_i32 v92, v203, 18, 1
	v_bfe_i32 v93, v203, 19, 1
	v_bfe_i32 v94, v203, 24, 1
	v_bfe_i32 v95, v203, 25, 1
	v_bfe_i32 v96, v203, 26, 1
	s_waitcnt lgkmcnt(7)
	v_mfma_f32_32x32x16_bf16 v[66:81], v[226:229], v[110:113], v[66:81]
	ds_read_b128 v[226:229], v217 offset:8800
	v_bfe_i32 v97, v203, 27, 1
	v_bfi_b32 v82, v82, v230, v231
	v_bfi_b32 v83, v83, v230, v231
	v_bfi_b32 v84, v84, v230, v231
	v_bfi_b32 v85, v85, v230, v231
	s_waitcnt lgkmcnt(7)
	v_mfma_f32_32x32x16_bf16 v[66:81], v[232:235], v[114:117], v[66:81]
	ds_read_b128 v[232:235], v217 offset:8832
	v_bfi_b32 v86, v86, v230, v231
	v_bfi_b32 v87, v87, v230, v231
	v_bfi_b32 v88, v88, v230, v231
	v_bfi_b32 v89, v89, v230, v231
	s_waitcnt lgkmcnt(7)
	v_mfma_f32_32x32x16_bf16 v[66:81], v[236:239], v[118:121], v[66:81]
	ds_read_b128 v[236:239], v217 offset:8864
	v_bfi_b32 v90, v90, v230, v231
	v_bfi_b32 v91, v91, v230, v231
	v_bfi_b32 v92, v92, v230, v231
	v_bfi_b32 v93, v93, v230, v231
	s_waitcnt lgkmcnt(7)
	v_mfma_f32_32x32x16_bf16 v[66:81], v[240:243], v[122:125], v[66:81]
	ds_read_b128 v[240:243], v217 offset:8896
	v_bfi_b32 v94, v94, v230, v231
	v_bfi_b32 v95, v95, v230, v231
	v_bfi_b32 v96, v96, v230, v231
	v_bfi_b32 v97, v97, v230, v231
	s_waitcnt lgkmcnt(7)
	v_mfma_f32_32x32x16_bf16 v[66:81], v[248:251], v[126:129], v[66:81]
	ds_read_b128 v[248:251], v217 offset:8928
	s_waitcnt lgkmcnt(7)
	v_mfma_f32_32x32x16_bf16 v[82:97], v[174:177], v[98:101], v[82:97]
	s_waitcnt lgkmcnt(6)
	v_mfma_f32_32x32x16_bf16 v[82:97], v[218:221], v[102:105], v[82:97]
	s_waitcnt lgkmcnt(5)
	v_mfma_f32_32x32x16_bf16 v[82:97], v[222:225], v[106:109], v[82:97]
	s_waitcnt lgkmcnt(4)
	v_mfma_f32_32x32x16_bf16 v[82:97], v[226:229], v[110:113], v[82:97]
	s_waitcnt lgkmcnt(3)
	v_mfma_f32_32x32x16_bf16 v[82:97], v[232:235], v[114:117], v[82:97]
	s_waitcnt lgkmcnt(2)
	v_mfma_f32_32x32x16_bf16 v[82:97], v[236:239], v[118:121], v[82:97]
	s_waitcnt lgkmcnt(1)
	v_mfma_f32_32x32x16_bf16 v[82:97], v[240:243], v[122:125], v[82:97]
	s_waitcnt lgkmcnt(0)
	v_mfma_f32_32x32x16_bf16 v[82:97], v[248:251], v[126:129], v[82:97]
	s_setprio 0

.LBB0_90:
	v_bfe_i32 v66, v218, 0, 1
	v_bfe_i32 v67, v218, 1, 1
	v_bfe_i32 v68, v218, 2, 1
	v_bfe_i32 v69, v218, 3, 1
	v_bfe_i32 v70, v218, 8, 1
	v_bfe_i32 v71, v218, 9, 1
	v_bfe_i32 v72, v218, 10, 1
	v_bfe_i32 v73, v218, 11, 1
	v_bfe_i32 v74, v218, 16, 1
	v_bfe_i32 v75, v218, 17, 1
	v_bfe_i32 v76, v218, 18, 1
	v_bfe_i32 v77, v218, 19, 1
	v_bfe_i32 v78, v218, 24, 1
	v_bfe_i32 v79, v218, 25, 1
	v_bfe_i32 v80, v218, 26, 1
	v_bfe_i32 v81, v218, 27, 1
	ds_read_b128 v[174:177], v217
	ds_read_b128 v[218:221], v217 offset:32
	ds_read_b128 v[222:225], v217 offset:64
	ds_read_b128 v[226:229], v217 offset:96
	ds_read_b128 v[232:235], v217 offset:128
	ds_read_b128 v[236:239], v217 offset:160
	ds_read_b128 v[240:243], v217 offset:192
	ds_read_b128 v[248:251], v217 offset:224
	v_bfi_b32 v66, v66, v230, v231
	v_bfi_b32 v67, v67, v230, v231
	v_bfi_b32 v68, v68, v230, v231
	v_bfi_b32 v69, v69, v230, v231
	v_bfi_b32 v70, v70, v230, v231
	v_bfi_b32 v71, v71, v230, v231
	v_bfi_b32 v72, v72, v230, v231
	v_bfi_b32 v73, v73, v230, v231
	v_bfi_b32 v74, v74, v230, v231
	v_bfi_b32 v75, v75, v230, v231
	v_bfi_b32 v76, v76, v230, v231
	v_bfi_b32 v77, v77, v230, v231
	v_bfi_b32 v78, v78, v230, v231
	v_bfi_b32 v79, v79, v230, v231
	v_bfi_b32 v80, v80, v230, v231
	v_bfi_b32 v81, v81, v230, v231
	s_setprio 1
	s_waitcnt lgkmcnt(7)
	v_mfma_f32_32x32x16_bf16 v[66:81], v[174:177], v[98:101], v[66:81]
	ds_read_b128 v[174:177], v217 offset:8704
	v_bfe_i32 v82, v205, 0, 1
	v_bfe_i32 v83, v205, 1, 1
	v_bfe_i32 v84, v205, 2, 1
	v_bfe_i32 v85, v205, 3, 1
	v_bfe_i32 v86, v205, 8, 1
	s_waitcnt lgkmcnt(7)
	v_mfma_f32_32x32x16_bf16 v[66:81], v[218:221], v[102:105], v[66:81]
	ds_read_b128 v[218:221], v217 offset:8736
	v_bfe_i32 v87, v205, 9, 1
	v_bfe_i32 v88, v205, 10, 1
	v_bfe_i32 v89, v205, 11, 1
	v_bfe_i32 v90, v205, 16, 1
	v_bfe_i32 v91, v205, 17, 1
	s_waitcnt lgkmcnt(7)
	v_mfma_f32_32x32x16_bf16 v[66:81], v[222:225], v[106:109], v[66:81]
	ds_read_b128 v[222:225], v217 offset:8768
	v_bfe_i32 v92, v205, 18, 1
	v_bfe_i32 v93, v205, 19, 1
	v_bfe_i32 v94, v205, 24, 1
	v_bfe_i32 v95, v205, 25, 1
	v_bfe_i32 v96, v205, 26, 1
	s_waitcnt lgkmcnt(7)
	v_mfma_f32_32x32x16_bf16 v[66:81], v[226:229], v[110:113], v[66:81]
	ds_read_b128 v[226:229], v217 offset:8800
	v_bfe_i32 v97, v205, 27, 1
	v_bfi_b32 v82, v82, v230, v231
	v_bfi_b32 v83, v83, v230, v231
	v_bfi_b32 v84, v84, v230, v231
	v_bfi_b32 v85, v85, v230, v231
	s_waitcnt lgkmcnt(7)
	v_mfma_f32_32x32x16_bf16 v[66:81], v[232:235], v[114:117], v[66:81]
	ds_read_b128 v[232:235], v217 offset:8832
	v_bfi_b32 v86, v86, v230, v231
	v_bfi_b32 v87, v87, v230, v231
	v_bfi_b32 v88, v88, v230, v231
	v_bfi_b32 v89, v89, v230, v231
	s_waitcnt lgkmcnt(7)
	v_mfma_f32_32x32x16_bf16 v[66:81], v[236:239], v[118:121], v[66:81]
	ds_read_b128 v[236:239], v217 offset:8864
	v_bfi_b32 v90, v90, v230, v231
	v_bfi_b32 v91, v91, v230, v231
	v_bfi_b32 v92, v92, v230, v231
	v_bfi_b32 v93, v93, v230, v231
	s_waitcnt lgkmcnt(7)
	v_mfma_f32_32x32x16_bf16 v[66:81], v[240:243], v[122:125], v[66:81]
	ds_read_b128 v[240:243], v217 offset:8896
	v_bfi_b32 v94, v94, v230, v231
	v_bfi_b32 v95, v95, v230, v231
	v_bfi_b32 v96, v96, v230, v231
	v_bfi_b32 v97, v97, v230, v231
	s_waitcnt lgkmcnt(7)
	v_mfma_f32_32x32x16_bf16 v[66:81], v[248:251], v[126:129], v[66:81]
	ds_read_b128 v[248:251], v217 offset:8928
	s_waitcnt lgkmcnt(7)
	v_mfma_f32_32x32x16_bf16 v[82:97], v[174:177], v[98:101], v[82:97]
	s_waitcnt lgkmcnt(6)
	v_mfma_f32_32x32x16_bf16 v[82:97], v[218:221], v[102:105], v[82:97]
	s_waitcnt lgkmcnt(5)
	v_mfma_f32_32x32x16_bf16 v[82:97], v[222:225], v[106:109], v[82:97]
	s_waitcnt lgkmcnt(4)
	v_mfma_f32_32x32x16_bf16 v[82:97], v[226:229], v[110:113], v[82:97]
	s_waitcnt lgkmcnt(3)
	v_mfma_f32_32x32x16_bf16 v[82:97], v[232:235], v[114:117], v[82:97]
	s_waitcnt lgkmcnt(2)
	v_mfma_f32_32x32x16_bf16 v[82:97], v[236:239], v[118:121], v[82:97]
	s_waitcnt lgkmcnt(1)
	v_mfma_f32_32x32x16_bf16 v[82:97], v[240:243], v[122:125], v[82:97]
	s_waitcnt lgkmcnt(0)
	v_mfma_f32_32x32x16_bf16 v[82:97], v[248:251], v[126:129], v[82:97]
	s_setprio 0
	v_max3_f32 v174, v231, v66, v82
	s_nop 0
	v_max3_f32 v174, v174, v67, v83
	s_nop 0
	v_max3_f32 v174, v174, v68, v84
	s_nop 0
	v_max3_f32 v174, v174, v69, v85
	s_nop 0
	v_max3_f32 v174, v174, v70, v86
	s_nop 0
	v_max3_f32 v174, v174, v71, v87
	s_nop 0
	v_max3_f32 v174, v174, v72, v88
	s_nop 0
	v_max3_f32 v174, v174, v73, v89
	s_nop 0
	v_max3_f32 v174, v174, v74, v90
	s_nop 0
	v_max3_f32 v174, v174, v75, v91
	s_nop 0
	v_max3_f32 v174, v174, v76, v92
	s_nop 0
	v_max3_f32 v174, v174, v77, v93
	s_nop 0
	v_max3_f32 v174, v174, v78, v94
	s_nop 0
	v_max3_f32 v174, v174, v79, v95
	s_nop 0
	v_max3_f32 v174, v174, v80, v96
	s_nop 0
	v_max3_f32 v174, v174, v81, v97
	s_nop 0
	v_mov_b32_e32 v175, v174
	s_nop 1
	v_permlane32_swap_b32_e32 v174, v175
	v_max_f32_e32 v174, v174, v175
	v_cmp_gt_f32_e32 vcc, v174, v245
	s_cmp_eq_u64 vcc, 0
	s_cbranch_scc1 .Lsmf_2
	v_cndmask_b32_e32 v193, 0, v174, vcc
	v_mov_b32_e32 v175, 0x41000000
	v_cndmask_b32_e32 v245, v245, v175, vcc
	v_sub_f32_e32 v230, v230, v193
	v_max_f32_e32 v175, 0, v193
	v_exp_f32_e64 v204, -v175
	s_nop 0
	v_pk_mul_f32 v[64:65], v[64:65], v[204:205] op_sel_hi:[1,0]
	v_pk_mul_f32 v[62:63], v[62:63], v[204:205] op_sel_hi:[1,0]
	v_pk_mul_f32 v[60:61], v[60:61], v[204:205] op_sel_hi:[1,0]
	v_pk_mul_f32 v[58:59], v[58:59], v[204:205] op_sel_hi:[1,0]
	v_pk_mul_f32 v[56:57], v[56:57], v[204:205] op_sel_hi:[1,0]
	v_pk_mul_f32 v[54:55], v[54:55], v[204:205] op_sel_hi:[1,0]
	v_pk_mul_f32 v[52:53], v[52:53], v[204:205] op_sel_hi:[1,0]
	v_pk_mul_f32 v[50:51], v[50:51], v[204:205] op_sel_hi:[1,0]
	v_pk_mul_f32 v[48:49], v[48:49], v[204:205] op_sel_hi:[1,0]
	v_pk_mul_f32 v[46:47], v[46:47], v[204:205] op_sel_hi:[1,0]
	v_pk_mul_f32 v[44:45], v[44:45], v[204:205] op_sel_hi:[1,0]
	v_pk_mul_f32 v[42:43], v[42:43], v[204:205] op_sel_hi:[1,0]
	v_pk_mul_f32 v[40:41], v[40:41], v[204:205] op_sel_hi:[1,0]
	v_pk_mul_f32 v[38:39], v[38:39], v[204:205] op_sel_hi:[1,0]
	v_pk_mul_f32 v[36:37], v[36:37], v[204:205] op_sel_hi:[1,0]
	v_pk_mul_f32 v[34:35], v[34:35], v[204:205] op_sel_hi:[1,0]
	v_pk_mul_f32 v[32:33], v[32:33], v[204:205] op_sel_hi:[1,0]
	v_pk_mul_f32 v[30:31], v[30:31], v[204:205] op_sel_hi:[1,0]
	v_pk_mul_f32 v[28:29], v[28:29], v[204:205] op_sel_hi:[1,0]
	v_pk_mul_f32 v[26:27], v[26:27], v[204:205] op_sel_hi:[1,0]
	v_pk_mul_f32 v[24:25], v[24:25], v[204:205] op_sel_hi:[1,0]
	v_pk_mul_f32 v[22:23], v[22:23], v[204:205] op_sel_hi:[1,0]
	v_pk_mul_f32 v[20:21], v[20:21], v[204:205] op_sel_hi:[1,0]
	v_pk_mul_f32 v[18:19], v[18:19], v[204:205] op_sel_hi:[1,0]
	v_pk_mul_f32 v[16:17], v[16:17], v[204:205] op_sel_hi:[1,0]
	v_pk_mul_f32 v[14:15], v[14:15], v[204:205] op_sel_hi:[1,0]
	v_pk_mul_f32 v[12:13], v[12:13], v[204:205] op_sel_hi:[1,0]
	v_pk_mul_f32 v[10:11], v[10:11], v[204:205] op_sel_hi:[1,0]
	v_pk_mul_f32 v[8:9], v[8:9], v[204:205] op_sel_hi:[1,0]
	v_pk_mul_f32 v[6:7], v[6:7], v[204:205] op_sel_hi:[1,0]
	v_pk_mul_f32 v[4:5], v[4:5], v[204:205] op_sel_hi:[1,0]
	v_pk_mul_f32 v[2:3], v[2:3], v[204:205] op_sel_hi:[1,0]

.Lsmj_3:
	v_add3_u32 v174, s47, v210, v211
	v_cvt_pk_bf16_f32 v66, v66, v67
	v_cvt_pk_bf16_f32 v67, v68, v69
	v_cvt_pk_bf16_f32 v68, v70, v71
	v_cvt_pk_bf16_f32 v69, v72, v73
	v_cvt_pk_bf16_f32 v70, v74, v75
	v_cvt_pk_bf16_f32 v71, v76, v77
	v_cvt_pk_bf16_f32 v72, v78, v79
	v_cvt_pk_bf16_f32 v73, v80, v81
	v_cvt_pk_bf16_f32 v74, v82, v83
	v_cvt_pk_bf16_f32 v75, v84, v85
	v_cvt_pk_bf16_f32 v76, v86, v87
	v_cvt_pk_bf16_f32 v77, v88, v89
	v_cvt_pk_bf16_f32 v78, v90, v91
	v_cvt_pk_bf16_f32 v79, v92, v93
	v_cvt_pk_bf16_f32 v80, v94, v95
	v_cvt_pk_bf16_f32 v81, v96, v97
	ds_read_b128 v[82:85], v174 offset:17408
	ds_read_b128 v[86:89], v174 offset:22016
	ds_read_b128 v[90:93], v174 offset:26624
	ds_read_b128 v[94:97], v174 offset:31232
	v_fmac_f32_e32 v193, v216, v204
	s_setprio 1
	s_waitcnt lgkmcnt(3)
	v_mfma_f32_32x32x16_bf16 v[50:65], v[82:85], v[66:69], v[50:65]
	s_waitcnt lgkmcnt(2)
	v_mfma_f32_32x32x16_bf16 v[34:49], v[86:89], v[66:69], v[34:49]
	s_waitcnt lgkmcnt(1)
	v_mfma_f32_32x32x16_bf16 v[18:33], v[90:93], v[66:69], v[18:33]
	s_waitcnt lgkmcnt(0)
	v_mfma_f32_32x32x16_bf16 v[2:17], v[94:97], v[66:69], v[2:17]
	s_setprio 0
	ds_read_b128 v[66:69], v174 offset:17440
	ds_read_b128 v[82:85], v174 offset:22048
	ds_read_b128 v[86:89], v174 offset:26656
	ds_read_b128 v[90:93], v174 offset:31264
	s_setprio 1
	s_waitcnt lgkmcnt(3)
	v_mfma_f32_32x32x16_bf16 v[50:65], v[66:69], v[70:73], v[50:65]
	s_waitcnt lgkmcnt(2)
	v_mfma_f32_32x32x16_bf16 v[34:49], v[82:85], v[70:73], v[34:49]
	s_waitcnt lgkmcnt(1)
	v_mfma_f32_32x32x16_bf16 v[18:33], v[86:89], v[70:73], v[18:33]
	s_waitcnt lgkmcnt(0)
	v_mfma_f32_32x32x16_bf16 v[2:17], v[90:93], v[70:73], v[2:17]
	s_setprio 0
	ds_read_b128 v[66:69], v174 offset:17472
	ds_read_b128 v[70:73], v174 offset:22080
	ds_read_b128 v[82:85], v174 offset:26688
	ds_read_b128 v[86:89], v174 offset:31296
	s_setprio 1
	s_waitcnt lgkmcnt(3)
	v_mfma_f32_32x32x16_bf16 v[50:65], v[66:69], v[74:77], v[50:65]
	s_waitcnt lgkmcnt(2)
	v_mfma_f32_32x32x16_bf16 v[34:49], v[70:73], v[74:77], v[34:49]
	s_waitcnt lgkmcnt(1)
	v_mfma_f32_32x32x16_bf16 v[18:33], v[82:85], v[74:77], v[18:33]
	s_waitcnt lgkmcnt(0)
	v_mfma_f32_32x32x16_bf16 v[2:17], v[86:89], v[74:77], v[2:17]
	s_setprio 0
	ds_read_b128 v[66:69], v174 offset:17504
	ds_read_b128 v[70:73], v174 offset:22112
	ds_read_b128 v[74:77], v174 offset:26720
	ds_read_b128 v[82:85], v174 offset:31328
	s_setprio 1
	s_waitcnt lgkmcnt(3)
	v_mfma_f32_32x32x16_bf16 v[50:65], v[66:69], v[78:81], v[50:65]
	s_waitcnt lgkmcnt(2)
	v_mfma_f32_32x32x16_bf16 v[34:49], v[70:73], v[78:81], v[34:49]
	s_waitcnt lgkmcnt(1)
	v_mfma_f32_32x32x16_bf16 v[18:33], v[74:77], v[78:81], v[18:33]
	s_waitcnt lgkmcnt(0)
	v_mfma_f32_32x32x16_bf16 v[2:17], v[82:85], v[78:81], v[2:17]
	s_setprio 0
	v_bfe_i32 v66, v218, 0, 1
	v_bfe_i32 v67, v218, 1, 1
	v_bfe_i32 v68, v218, 2, 1
	v_bfe_i32 v69, v218, 3, 1
	v_bfe_i32 v70, v218, 8, 1
	v_bfe_i32 v71, v218, 9, 1
	v_bfe_i32 v72, v218, 10, 1
	v_bfe_i32 v73, v218, 11, 1
	v_bfe_i32 v74, v218, 16, 1
	v_bfe_i32 v75, v218, 17, 1
	v_bfe_i32 v76, v218, 18, 1
	v_bfe_i32 v77, v218, 19, 1
	v_bfe_i32 v78, v218, 24, 1
	v_bfe_i32 v79, v218, 25, 1
	v_bfe_i32 v80, v218, 26, 1
	v_bfe_i32 v81, v218, 27, 1
	ds_read_b128 v[174:177], v217
	ds_read_b128 v[218:221], v217 offset:32
	ds_read_b128 v[222:225], v217 offset:64
	ds_read_b128 v[226:229], v217 offset:96
	ds_read_b128 v[232:235], v217 offset:128
	ds_read_b128 v[236:239], v217 offset:160
	ds_read_b128 v[240:243], v217 offset:192
	ds_read_b128 v[248:251], v217 offset:224
	v_bfi_b32 v66, v66, v230, v231
	v_bfi_b32 v67, v67, v230, v231
	v_bfi_b32 v68, v68, v230, v231
	v_bfi_b32 v69, v69, v230, v231
	v_bfi_b32 v70, v70, v230, v231
	v_bfi_b32 v71, v71, v230, v231
	v_bfi_b32 v72, v72, v230, v231
	v_bfi_b32 v73, v73, v230, v231
	v_bfi_b32 v74, v74, v230, v231
	v_bfi_b32 v75, v75, v230, v231
	v_bfi_b32 v76, v76, v230, v231
	v_bfi_b32 v77, v77, v230, v231
	v_bfi_b32 v78, v78, v230, v231
	v_bfi_b32 v79, v79, v230, v231
	v_bfi_b32 v80, v80, v230, v231
	v_bfi_b32 v81, v81, v230, v231
	s_setprio 1
	s_waitcnt lgkmcnt(7)
	v_mfma_f32_32x32x16_bf16 v[66:81], v[174:177], v[98:101], v[66:81]
	ds_read_b128 v[174:177], v217 offset:8704
	v_bfe_i32 v82, v205, 0, 1
	v_bfe_i32 v83, v205, 1, 1
	v_bfe_i32 v84, v205, 2, 1
	v_bfe_i32 v85, v205, 3, 1
	v_bfe_i32 v86, v205, 8, 1
	s_waitcnt lgkmcnt(7)
	v_mfma_f32_32x32x16_bf16 v[66:81], v[218:221], v[102:105], v[66:81]
	ds_read_b128 v[218:221], v217 offset:8736
	v_bfe_i32 v87, v205, 9, 1
	v_bfe_i32 v88, v205, 10, 1
	v_bfe_i32 v89, v205, 11, 1
	v_bfe_i32 v90, v205, 16, 1
	v_bfe_i32 v91, v205, 17, 1
	s_waitcnt lgkmcnt(7)
	v_mfma_f32_32x32x16_bf16 v[66:81], v[222:225], v[106:109], v[66:81]
	ds_read_b128 v[222:225], v217 offset:8768
	v_bfe_i32 v92, v205, 18, 1
	v_bfe_i32 v93, v205, 19, 1
	v_bfe_i32 v94, v205, 24, 1
	v_bfe_i32 v95, v205, 25, 1
	v_bfe_i32 v96, v205, 26, 1
	s_waitcnt lgkmcnt(7)
	v_mfma_f32_32x32x16_bf16 v[66:81], v[226:229], v[110:113], v[66:81]
	ds_read_b128 v[226:229], v217 offset:8800
	v_bfe_i32 v97, v205, 27, 1
	v_bfi_b32 v82, v82, v230, v231
	v_bfi_b32 v83, v83, v230, v231
	v_bfi_b32 v84, v84, v230, v231
	v_bfi_b32 v85, v85, v230, v231
	s_waitcnt lgkmcnt(7)
	v_mfma_f32_32x32x16_bf16 v[66:81], v[232:235], v[114:117], v[66:81]
	ds_read_b128 v[232:235], v217 offset:8832
	v_bfi_b32 v86, v86, v230, v231
	v_bfi_b32 v87, v87, v230, v231
	v_bfi_b32 v88, v88, v230, v231
	v_bfi_b32 v89, v89, v230, v231
	s_waitcnt lgkmcnt(7)
	v_mfma_f32_32x32x16_bf16 v[66:81], v[236:239], v[118:121], v[66:81]
	ds_read_b128 v[236:239], v217 offset:8864
	v_bfi_b32 v90, v90, v230, v231
	v_bfi_b32 v91, v91, v230, v231
	v_bfi_b32 v92, v92, v230, v231
	v_bfi_b32 v93, v93, v230, v231
	s_waitcnt lgkmcnt(7)
	v_mfma_f32_32x32x16_bf16 v[66:81], v[240:243], v[122:125], v[66:81]
	ds_read_b128 v[240:243], v217 offset:8896
	v_bfi_b32 v94, v94, v230, v231
	v_bfi_b32 v95, v95, v230, v231
	v_bfi_b32 v96, v96, v230, v231
	v_bfi_b32 v97, v97, v230, v231
	s_waitcnt lgkmcnt(7)
	v_mfma_f32_32x32x16_bf16 v[66:81], v[248:251], v[126:129], v[66:81]
	ds_read_b128 v[248:251], v217 offset:8928
	s_waitcnt lgkmcnt(7)
	v_mfma_f32_32x32x16_bf16 v[82:97], v[174:177], v[98:101], v[82:97]
	s_waitcnt lgkmcnt(6)
	v_mfma_f32_32x32x16_bf16 v[82:97], v[218:221], v[102:105], v[82:97]
	s_waitcnt lgkmcnt(5)
	v_mfma_f32_32x32x16_bf16 v[82:97], v[222:225], v[106:109], v[82:97]
	s_waitcnt lgkmcnt(4)
	v_mfma_f32_32x32x16_bf16 v[82:97], v[226:229], v[110:113], v[82:97]
	s_waitcnt lgkmcnt(3)
	v_mfma_f32_32x32x16_bf16 v[82:97], v[232:235], v[114:117], v[82:97]
	s_waitcnt lgkmcnt(2)
	v_mfma_f32_32x32x16_bf16 v[82:97], v[236:239], v[118:121], v[82:97]
	s_waitcnt lgkmcnt(1)
	v_mfma_f32_32x32x16_bf16 v[82:97], v[240:243], v[122:125], v[82:97]
	s_waitcnt lgkmcnt(0)
	v_mfma_f32_32x32x16_bf16 v[82:97], v[248:251], v[126:129], v[82:97]
	s_setprio 0
	s_or_b64 exec, exec, s[0:1]
	s_and_b64 vcc, exec, s[8:9]
	s_cbranch_vccz .LBB0_88
	s_branch .LBB0_89
